# grid barrier: XCC leader no longer performs the unused per-XCC generation relay atomic (on v52)
# speedup vs baseline: 1.0034x; 1.0034x over previous
.LBB0_755:
	s_or_b64 exec, exec, s[8:9]
	v_readlane_b32 s8, v254, 19
	v_readlane_b32 s9, v254, 20
	v_mov_b32_e32 v0, 1
	s_waitcnt vmcnt(0)
	buffer_inv sc1
	s_nop 1
	s_waitcnt vmcnt(0)
